# phase 7 rstd rows: 8 rows and all 32 row loads in flight per wave, batched butterfly
# baseline (speedup 1.0000x reference)
; __device__ __forceinline__ float bflo(unsigned w) { return __uint_as_float(w << 16); }
; __device__ __forceinline__ float bfhi(unsigned w) { return __uint_as_float(w & 0xffff0000u); }
; __device__ __forceinline__ void rstd_rows_b(const bf16* __restrict__ X, float* __restrict__ R, int gw, int NGW, int lane) {
;     for (int m = gw; m < S_; m += NGW) {
;         const v4u* xr = (const v4u*)(X + (size_t)m * DM) + lane; float s = 0.f;
; #pragma unroll
;         for (int j = 0; j < 4; ++j) { const v4u w = xr[64 * j];
;             const float a0 = bflo(w.x), a1 = bfhi(w.x), a2 = bflo(w.y), a3 = bfhi(w.y), a4 = bflo(w.z), a5 = bfhi(w.z), a6 = bflo(w.w), a7 = bfhi(w.w);
;             s += (a0 * a0 + a1 * a1) + (a2 * a2 + a3 * a3) + (a4 * a4 + a5 * a5) + (a6 * a6 + a7 * a7); }
;         const float rstd = 1.f / sqrtf(wave_sum(s) * (1.f / DM) + EPS_);
;         if (lane == 0) R[m] = rstd;
;     }
; }
.Lrstd7_batch:
	v_readfirstlane_b32 s10, v3
	v_readfirstlane_b32 s11, v2
	s_nop 3
	s_mul_i32 s12, s11, 7
	s_add_i32 s12, s12, s10
	s_cmpk_lt_i32 s12, 0x4000
	s_cbranch_scc0 .LBB0_1666
	global_load_dwordx4 v[32:35], v[6:7], off offset:-2048
	global_load_dwordx4 v[36:39], v[6:7], off offset:-1024
	global_load_dwordx4 v[40:43], v[6:7], off
	global_load_dwordx4 v[44:47], v[6:7], off offset:1024
	v_lshl_add_u64 v[22:23], v[6:7], 0, v[8:9]
	global_load_dwordx4 v[48:51], v[22:23], off offset:-2048
	global_load_dwordx4 v[52:55], v[22:23], off offset:-1024
	global_load_dwordx4 v[56:59], v[22:23], off
	global_load_dwordx4 v[60:63], v[22:23], off offset:1024
	v_lshl_add_u64 v[20:21], v[22:23], 0, v[8:9]
	global_load_dwordx4 v[64:67], v[20:21], off offset:-2048
	global_load_dwordx4 v[68:71], v[20:21], off offset:-1024
	global_load_dwordx4 v[72:75], v[20:21], off
	global_load_dwordx4 v[76:79], v[20:21], off offset:1024
	v_lshl_add_u64 v[22:23], v[20:21], 0, v[8:9]
	global_load_dwordx4 v[80:83], v[22:23], off offset:-2048
	global_load_dwordx4 v[84:87], v[22:23], off offset:-1024
	global_load_dwordx4 v[88:91], v[22:23], off
	global_load_dwordx4 v[92:95], v[22:23], off offset:1024
	v_lshl_add_u64 v[20:21], v[22:23], 0, v[8:9]
	global_load_dwordx4 v[96:99], v[20:21], off offset:-2048
	global_load_dwordx4 v[100:103], v[20:21], off offset:-1024
	global_load_dwordx4 v[104:107], v[20:21], off
	global_load_dwordx4 v[108:111], v[20:21], off offset:1024
	v_lshl_add_u64 v[22:23], v[20:21], 0, v[8:9]
	global_load_dwordx4 v[112:115], v[22:23], off offset:-2048
	global_load_dwordx4 v[116:119], v[22:23], off offset:-1024
	global_load_dwordx4 v[120:123], v[22:23], off
	global_load_dwordx4 v[124:127], v[22:23], off offset:1024
	v_lshl_add_u64 v[20:21], v[22:23], 0, v[8:9]
	global_load_dwordx4 v[128:131], v[20:21], off offset:-2048
	global_load_dwordx4 v[132:135], v[20:21], off offset:-1024
	global_load_dwordx4 v[136:139], v[20:21], off
	global_load_dwordx4 v[140:143], v[20:21], off offset:1024
	v_lshl_add_u64 v[22:23], v[20:21], 0, v[8:9]
	global_load_dwordx4 v[144:147], v[22:23], off offset:-2048
	global_load_dwordx4 v[148:151], v[22:23], off offset:-1024
	global_load_dwordx4 v[152:155], v[22:23], off
	global_load_dwordx4 v[156:159], v[22:23], off offset:1024
	s_waitcnt vmcnt(28)
	v_lshlrev_b32_e32 v182, 16, v32
	v_and_b32_e32 v183, 0xffff0000, v32
	v_mul_f32_e32 v184, v183, v183
	v_fmac_f32_e32 v184, v182, v182
	v_lshlrev_b32_e32 v182, 16, v33
	v_and_b32_e32 v183, 0xffff0000, v33
	v_mul_f32_e32 v185, v183, v183
	v_fmac_f32_e32 v185, v182, v182
	v_add_f32_e32 v24, v184, v185
	v_lshlrev_b32_e32 v182, 16, v34
	v_and_b32_e32 v183, 0xffff0000, v34
	v_mul_f32_e32 v184, v183, v183
	v_fmac_f32_e32 v184, v182, v182
	v_add_f32_e32 v24, v184, v24
	v_lshlrev_b32_e32 v182, 16, v35
	v_and_b32_e32 v183, 0xffff0000, v35
	v_mul_f32_e32 v184, v183, v183
	v_fmac_f32_e32 v184, v182, v182
	v_add_f32_e32 v24, v184, v24
	v_lshlrev_b32_e32 v182, 16, v36
	v_and_b32_e32 v183, 0xffff0000, v36
	v_mul_f32_e32 v184, v183, v183
	v_fmac_f32_e32 v184, v182, v182
	v_lshlrev_b32_e32 v182, 16, v37
	v_and_b32_e32 v183, 0xffff0000, v37
	v_mul_f32_e32 v185, v183, v183
	v_fmac_f32_e32 v185, v182, v182
	v_add_f32_e32 v186, v184, v185
	v_lshlrev_b32_e32 v182, 16, v38
	v_and_b32_e32 v183, 0xffff0000, v38
	v_mul_f32_e32 v184, v183, v183
	v_fmac_f32_e32 v184, v182, v182
	v_add_f32_e32 v186, v184, v186
	v_lshlrev_b32_e32 v182, 16, v39
	v_and_b32_e32 v183, 0xffff0000, v39
	v_mul_f32_e32 v184, v183, v183
	v_fmac_f32_e32 v184, v182, v182
	v_add_f32_e32 v186, v184, v186
	v_add_f32_e32 v24, v24, v186
	v_lshlrev_b32_e32 v182, 16, v40
	v_and_b32_e32 v183, 0xffff0000, v40
	v_mul_f32_e32 v184, v183, v183
	v_fmac_f32_e32 v184, v182, v182
	v_lshlrev_b32_e32 v182, 16, v41
	v_and_b32_e32 v183, 0xffff0000, v41
	v_mul_f32_e32 v185, v183, v183
	v_fmac_f32_e32 v185, v182, v182
	v_add_f32_e32 v186, v184, v185
	v_lshlrev_b32_e32 v182, 16, v42
	v_and_b32_e32 v183, 0xffff0000, v42
	v_mul_f32_e32 v184, v183, v183
	v_fmac_f32_e32 v184, v182, v182
	v_add_f32_e32 v186, v184, v186
	v_lshlrev_b32_e32 v182, 16, v43
	v_and_b32_e32 v183, 0xffff0000, v43
	v_mul_f32_e32 v184, v183, v183
	v_fmac_f32_e32 v184, v182, v182
	v_add_f32_e32 v186, v184, v186
	v_add_f32_e32 v24, v24, v186
	v_lshlrev_b32_e32 v182, 16, v44
	v_and_b32_e32 v183, 0xffff0000, v44
	v_mul_f32_e32 v184, v183, v183
	v_fmac_f32_e32 v184, v182, v182
	v_lshlrev_b32_e32 v182, 16, v45
	v_and_b32_e32 v183, 0xffff0000, v45
	v_mul_f32_e32 v185, v183, v183
	v_fmac_f32_e32 v185, v182, v182
	v_add_f32_e32 v186, v184, v185
	v_lshlrev_b32_e32 v182, 16, v46
	v_and_b32_e32 v183, 0xffff0000, v46
	v_mul_f32_e32 v184, v183, v183
	v_fmac_f32_e32 v184, v182, v182
	v_add_f32_e32 v186, v184, v186
	v_lshlrev_b32_e32 v182, 16, v47
	v_and_b32_e32 v183, 0xffff0000, v47
	v_mul_f32_e32 v184, v183, v183
	v_fmac_f32_e32 v184, v182, v182
	v_add_f32_e32 v186, v184, v186
	v_add_f32_e32 v24, v24, v186
	s_waitcnt vmcnt(24)
; __device__ __forceinline__ float bflo(unsigned w) { return __uint_as_float(w << 16); }
; __device__ __forceinline__ float bfhi(unsigned w) { return __uint_as_float(w & 0xffff0000u); }
; __device__ __forceinline__ void rstd_rows_b(const bf16* __restrict__ X, float* __restrict__ R, int gw, int NGW, int lane) {
;     for (int m = gw; m < S_; m += NGW) {
;         const v4u* xr = (const v4u*)(X + (size_t)m * DM) + lane; float s = 0.f;
; #pragma unroll
;         for (int j = 0; j < 4; ++j) { const v4u w = xr[64 * j];
;             const float a0 = bflo(w.x), a1 = bfhi(w.x), a2 = bflo(w.y), a3 = bfhi(w.y), a4 = bflo(w.z), a5 = bfhi(w.z), a6 = bflo(w.w), a7 = bfhi(w.w);
;             s += (a0 * a0 + a1 * a1) + (a2 * a2 + a3 * a3) + (a4 * a4 + a5 * a5) + (a6 * a6 + a7 * a7); }
;         const float rstd = 1.f / sqrtf(wave_sum(s) * (1.f / DM) + EPS_);
;         if (lane == 0) R[m] = rstd;
;     }
; }
	v_lshlrev_b32_e32 v182, 16, v48
	v_and_b32_e32 v183, 0xffff0000, v48
	v_mul_f32_e32 v184, v183, v183
	v_fmac_f32_e32 v184, v182, v182
	v_lshlrev_b32_e32 v182, 16, v49
	v_and_b32_e32 v183, 0xffff0000, v49
	v_mul_f32_e32 v185, v183, v183
	v_fmac_f32_e32 v185, v182, v182
	v_add_f32_e32 v25, v184, v185
	v_lshlrev_b32_e32 v182, 16, v50
	v_and_b32_e32 v183, 0xffff0000, v50
	v_mul_f32_e32 v184, v183, v183
	v_fmac_f32_e32 v184, v182, v182
	v_add_f32_e32 v25, v184, v25
	v_lshlrev_b32_e32 v182, 16, v51
	v_and_b32_e32 v183, 0xffff0000, v51
	v_mul_f32_e32 v184, v183, v183
	v_fmac_f32_e32 v184, v182, v182
	v_add_f32_e32 v25, v184, v25
	v_lshlrev_b32_e32 v182, 16, v52
	v_and_b32_e32 v183, 0xffff0000, v52
	v_mul_f32_e32 v184, v183, v183
	v_fmac_f32_e32 v184, v182, v182
	v_lshlrev_b32_e32 v182, 16, v53
	v_and_b32_e32 v183, 0xffff0000, v53
	v_mul_f32_e32 v185, v183, v183
	v_fmac_f32_e32 v185, v182, v182
	v_add_f32_e32 v186, v184, v185
	v_lshlrev_b32_e32 v182, 16, v54
	v_and_b32_e32 v183, 0xffff0000, v54
	v_mul_f32_e32 v184, v183, v183
	v_fmac_f32_e32 v184, v182, v182
	v_add_f32_e32 v186, v184, v186
	v_lshlrev_b32_e32 v182, 16, v55
	v_and_b32_e32 v183, 0xffff0000, v55
	v_mul_f32_e32 v184, v183, v183
	v_fmac_f32_e32 v184, v182, v182
	v_add_f32_e32 v186, v184, v186
	v_add_f32_e32 v25, v25, v186
	v_lshlrev_b32_e32 v182, 16, v56
	v_and_b32_e32 v183, 0xffff0000, v56
	v_mul_f32_e32 v184, v183, v183
	v_fmac_f32_e32 v184, v182, v182
	v_lshlrev_b32_e32 v182, 16, v57
	v_and_b32_e32 v183, 0xffff0000, v57
	v_mul_f32_e32 v185, v183, v183
	v_fmac_f32_e32 v185, v182, v182
	v_add_f32_e32 v186, v184, v185
	v_lshlrev_b32_e32 v182, 16, v58
	v_and_b32_e32 v183, 0xffff0000, v58
	v_mul_f32_e32 v184, v183, v183
	v_fmac_f32_e32 v184, v182, v182
	v_add_f32_e32 v186, v184, v186
	v_lshlrev_b32_e32 v182, 16, v59
	v_and_b32_e32 v183, 0xffff0000, v59
	v_mul_f32_e32 v184, v183, v183
	v_fmac_f32_e32 v184, v182, v182
	v_add_f32_e32 v186, v184, v186
	v_add_f32_e32 v25, v25, v186
	v_lshlrev_b32_e32 v182, 16, v60
	v_and_b32_e32 v183, 0xffff0000, v60
	v_mul_f32_e32 v184, v183, v183
	v_fmac_f32_e32 v184, v182, v182
	v_lshlrev_b32_e32 v182, 16, v61
	v_and_b32_e32 v183, 0xffff0000, v61
	v_mul_f32_e32 v185, v183, v183
	v_fmac_f32_e32 v185, v182, v182
	v_add_f32_e32 v186, v184, v185
	v_lshlrev_b32_e32 v182, 16, v62
	v_and_b32_e32 v183, 0xffff0000, v62
	v_mul_f32_e32 v184, v183, v183
	v_fmac_f32_e32 v184, v182, v182
	v_add_f32_e32 v186, v184, v186
	v_lshlrev_b32_e32 v182, 16, v63
	v_and_b32_e32 v183, 0xffff0000, v63
	v_mul_f32_e32 v184, v183, v183
	v_fmac_f32_e32 v184, v182, v182
	v_add_f32_e32 v186, v184, v186
	v_add_f32_e32 v25, v25, v186
	s_waitcnt vmcnt(20)
	v_lshlrev_b32_e32 v182, 16, v64
	v_and_b32_e32 v183, 0xffff0000, v64
	v_mul_f32_e32 v184, v183, v183
	v_fmac_f32_e32 v184, v182, v182
	v_lshlrev_b32_e32 v182, 16, v65
	v_and_b32_e32 v183, 0xffff0000, v65
	v_mul_f32_e32 v185, v183, v183
	v_fmac_f32_e32 v185, v182, v182
	v_add_f32_e32 v26, v184, v185
	v_lshlrev_b32_e32 v182, 16, v66
	v_and_b32_e32 v183, 0xffff0000, v66
	v_mul_f32_e32 v184, v183, v183
	v_fmac_f32_e32 v184, v182, v182
	v_add_f32_e32 v26, v184, v26
	v_lshlrev_b32_e32 v182, 16, v67
	v_and_b32_e32 v183, 0xffff0000, v67
	v_mul_f32_e32 v184, v183, v183
	v_fmac_f32_e32 v184, v182, v182
	v_add_f32_e32 v26, v184, v26
	v_lshlrev_b32_e32 v182, 16, v68
	v_and_b32_e32 v183, 0xffff0000, v68
	v_mul_f32_e32 v184, v183, v183
	v_fmac_f32_e32 v184, v182, v182
	v_lshlrev_b32_e32 v182, 16, v69
	v_and_b32_e32 v183, 0xffff0000, v69
	v_mul_f32_e32 v185, v183, v183
	v_fmac_f32_e32 v185, v182, v182
	v_add_f32_e32 v186, v184, v185
	v_lshlrev_b32_e32 v182, 16, v70
	v_and_b32_e32 v183, 0xffff0000, v70
	v_mul_f32_e32 v184, v183, v183
	v_fmac_f32_e32 v184, v182, v182
	v_add_f32_e32 v186, v184, v186
	v_lshlrev_b32_e32 v182, 16, v71
	v_and_b32_e32 v183, 0xffff0000, v71
	v_mul_f32_e32 v184, v183, v183
	v_fmac_f32_e32 v184, v182, v182
	v_add_f32_e32 v186, v184, v186
	v_add_f32_e32 v26, v26, v186
	v_lshlrev_b32_e32 v182, 16, v72
	v_and_b32_e32 v183, 0xffff0000, v72
	v_mul_f32_e32 v184, v183, v183
	v_fmac_f32_e32 v184, v182, v182
	v_lshlrev_b32_e32 v182, 16, v73
	v_and_b32_e32 v183, 0xffff0000, v73
	v_mul_f32_e32 v185, v183, v183
	v_fmac_f32_e32 v185, v182, v182
	v_add_f32_e32 v186, v184, v185
	v_lshlrev_b32_e32 v182, 16, v74
	v_and_b32_e32 v183, 0xffff0000, v74
	v_mul_f32_e32 v184, v183, v183
	v_fmac_f32_e32 v184, v182, v182
	v_add_f32_e32 v186, v184, v186
	v_lshlrev_b32_e32 v182, 16, v75
	v_and_b32_e32 v183, 0xffff0000, v75
	v_mul_f32_e32 v184, v183, v183
	v_fmac_f32_e32 v184, v182, v182
	v_add_f32_e32 v186, v184, v186
	v_add_f32_e32 v26, v26, v186
	v_lshlrev_b32_e32 v182, 16, v76
	v_and_b32_e32 v183, 0xffff0000, v76
	v_mul_f32_e32 v184, v183, v183
	v_fmac_f32_e32 v184, v182, v182
	v_lshlrev_b32_e32 v182, 16, v77
	v_and_b32_e32 v183, 0xffff0000, v77
	v_mul_f32_e32 v185, v183, v183
	v_fmac_f32_e32 v185, v182, v182
	v_add_f32_e32 v186, v184, v185
	v_lshlrev_b32_e32 v182, 16, v78
	v_and_b32_e32 v183, 0xffff0000, v78
	v_mul_f32_e32 v184, v183, v183
	v_fmac_f32_e32 v184, v182, v182
	v_add_f32_e32 v186, v184, v186
	v_lshlrev_b32_e32 v182, 16, v79
	v_and_b32_e32 v183, 0xffff0000, v79
	v_mul_f32_e32 v184, v183, v183
	v_fmac_f32_e32 v184, v182, v182
	v_add_f32_e32 v186, v184, v186
	v_add_f32_e32 v26, v26, v186
	s_waitcnt vmcnt(16)
; __device__ __forceinline__ float bflo(unsigned w) { return __uint_as_float(w << 16); }
; __device__ __forceinline__ float bfhi(unsigned w) { return __uint_as_float(w & 0xffff0000u); }
; __device__ __forceinline__ void rstd_rows_b(const bf16* __restrict__ X, float* __restrict__ R, int gw, int NGW, int lane) {
;     for (int m = gw; m < S_; m += NGW) {
;         const v4u* xr = (const v4u*)(X + (size_t)m * DM) + lane; float s = 0.f;
; #pragma unroll
;         for (int j = 0; j < 4; ++j) { const v4u w = xr[64 * j];
;             const float a0 = bflo(w.x), a1 = bfhi(w.x), a2 = bflo(w.y), a3 = bfhi(w.y), a4 = bflo(w.z), a5 = bfhi(w.z), a6 = bflo(w.w), a7 = bfhi(w.w);
;             s += (a0 * a0 + a1 * a1) + (a2 * a2 + a3 * a3) + (a4 * a4 + a5 * a5) + (a6 * a6 + a7 * a7); }
;         const float rstd = 1.f / sqrtf(wave_sum(s) * (1.f / DM) + EPS_);
;         if (lane == 0) R[m] = rstd;
;     }
; }
	v_lshlrev_b32_e32 v182, 16, v80
	v_and_b32_e32 v183, 0xffff0000, v80
	v_mul_f32_e32 v184, v183, v183
	v_fmac_f32_e32 v184, v182, v182
	v_lshlrev_b32_e32 v182, 16, v81
	v_and_b32_e32 v183, 0xffff0000, v81
	v_mul_f32_e32 v185, v183, v183
	v_fmac_f32_e32 v185, v182, v182
	v_add_f32_e32 v27, v184, v185
	v_lshlrev_b32_e32 v182, 16, v82
	v_and_b32_e32 v183, 0xffff0000, v82
	v_mul_f32_e32 v184, v183, v183
	v_fmac_f32_e32 v184, v182, v182
	v_add_f32_e32 v27, v184, v27
	v_lshlrev_b32_e32 v182, 16, v83
	v_and_b32_e32 v183, 0xffff0000, v83
	v_mul_f32_e32 v184, v183, v183
	v_fmac_f32_e32 v184, v182, v182
	v_add_f32_e32 v27, v184, v27
	v_lshlrev_b32_e32 v182, 16, v84
	v_and_b32_e32 v183, 0xffff0000, v84
	v_mul_f32_e32 v184, v183, v183
	v_fmac_f32_e32 v184, v182, v182
	v_lshlrev_b32_e32 v182, 16, v85
	v_and_b32_e32 v183, 0xffff0000, v85
	v_mul_f32_e32 v185, v183, v183
	v_fmac_f32_e32 v185, v182, v182
	v_add_f32_e32 v186, v184, v185
	v_lshlrev_b32_e32 v182, 16, v86
	v_and_b32_e32 v183, 0xffff0000, v86
	v_mul_f32_e32 v184, v183, v183
	v_fmac_f32_e32 v184, v182, v182
	v_add_f32_e32 v186, v184, v186
	v_lshlrev_b32_e32 v182, 16, v87
	v_and_b32_e32 v183, 0xffff0000, v87
	v_mul_f32_e32 v184, v183, v183
	v_fmac_f32_e32 v184, v182, v182
	v_add_f32_e32 v186, v184, v186
	v_add_f32_e32 v27, v27, v186
	v_lshlrev_b32_e32 v182, 16, v88
	v_and_b32_e32 v183, 0xffff0000, v88
	v_mul_f32_e32 v184, v183, v183
	v_fmac_f32_e32 v184, v182, v182
	v_lshlrev_b32_e32 v182, 16, v89
	v_and_b32_e32 v183, 0xffff0000, v89
	v_mul_f32_e32 v185, v183, v183
	v_fmac_f32_e32 v185, v182, v182
	v_add_f32_e32 v186, v184, v185
	v_lshlrev_b32_e32 v182, 16, v90
	v_and_b32_e32 v183, 0xffff0000, v90
	v_mul_f32_e32 v184, v183, v183
	v_fmac_f32_e32 v184, v182, v182
	v_add_f32_e32 v186, v184, v186
	v_lshlrev_b32_e32 v182, 16, v91
	v_and_b32_e32 v183, 0xffff0000, v91
	v_mul_f32_e32 v184, v183, v183
	v_fmac_f32_e32 v184, v182, v182
	v_add_f32_e32 v186, v184, v186
	v_add_f32_e32 v27, v27, v186
	v_lshlrev_b32_e32 v182, 16, v92
	v_and_b32_e32 v183, 0xffff0000, v92
	v_mul_f32_e32 v184, v183, v183
	v_fmac_f32_e32 v184, v182, v182
	v_lshlrev_b32_e32 v182, 16, v93
	v_and_b32_e32 v183, 0xffff0000, v93
	v_mul_f32_e32 v185, v183, v183
	v_fmac_f32_e32 v185, v182, v182
	v_add_f32_e32 v186, v184, v185
	v_lshlrev_b32_e32 v182, 16, v94
	v_and_b32_e32 v183, 0xffff0000, v94
	v_mul_f32_e32 v184, v183, v183
	v_fmac_f32_e32 v184, v182, v182
	v_add_f32_e32 v186, v184, v186
	v_lshlrev_b32_e32 v182, 16, v95
	v_and_b32_e32 v183, 0xffff0000, v95
	v_mul_f32_e32 v184, v183, v183
	v_fmac_f32_e32 v184, v182, v182
	v_add_f32_e32 v186, v184, v186
	v_add_f32_e32 v27, v27, v186
	s_waitcnt vmcnt(12)
	v_lshlrev_b32_e32 v182, 16, v96
	v_and_b32_e32 v183, 0xffff0000, v96
	v_mul_f32_e32 v184, v183, v183
	v_fmac_f32_e32 v184, v182, v182
	v_lshlrev_b32_e32 v182, 16, v97
	v_and_b32_e32 v183, 0xffff0000, v97
	v_mul_f32_e32 v185, v183, v183
	v_fmac_f32_e32 v185, v182, v182
	v_add_f32_e32 v28, v184, v185
	v_lshlrev_b32_e32 v182, 16, v98
	v_and_b32_e32 v183, 0xffff0000, v98
	v_mul_f32_e32 v184, v183, v183
	v_fmac_f32_e32 v184, v182, v182
	v_add_f32_e32 v28, v184, v28
	v_lshlrev_b32_e32 v182, 16, v99
	v_and_b32_e32 v183, 0xffff0000, v99
	v_mul_f32_e32 v184, v183, v183
	v_fmac_f32_e32 v184, v182, v182
	v_add_f32_e32 v28, v184, v28
	v_lshlrev_b32_e32 v182, 16, v100
	v_and_b32_e32 v183, 0xffff0000, v100
	v_mul_f32_e32 v184, v183, v183
	v_fmac_f32_e32 v184, v182, v182
	v_lshlrev_b32_e32 v182, 16, v101
	v_and_b32_e32 v183, 0xffff0000, v101
	v_mul_f32_e32 v185, v183, v183
	v_fmac_f32_e32 v185, v182, v182
	v_add_f32_e32 v186, v184, v185
	v_lshlrev_b32_e32 v182, 16, v102
	v_and_b32_e32 v183, 0xffff0000, v102
	v_mul_f32_e32 v184, v183, v183
	v_fmac_f32_e32 v184, v182, v182
	v_add_f32_e32 v186, v184, v186
	v_lshlrev_b32_e32 v182, 16, v103
	v_and_b32_e32 v183, 0xffff0000, v103
	v_mul_f32_e32 v184, v183, v183
	v_fmac_f32_e32 v184, v182, v182
	v_add_f32_e32 v186, v184, v186
	v_add_f32_e32 v28, v28, v186
	v_lshlrev_b32_e32 v182, 16, v104
	v_and_b32_e32 v183, 0xffff0000, v104
	v_mul_f32_e32 v184, v183, v183
	v_fmac_f32_e32 v184, v182, v182
	v_lshlrev_b32_e32 v182, 16, v105
	v_and_b32_e32 v183, 0xffff0000, v105
	v_mul_f32_e32 v185, v183, v183
	v_fmac_f32_e32 v185, v182, v182
	v_add_f32_e32 v186, v184, v185
	v_lshlrev_b32_e32 v182, 16, v106
	v_and_b32_e32 v183, 0xffff0000, v106
	v_mul_f32_e32 v184, v183, v183
	v_fmac_f32_e32 v184, v182, v182
	v_add_f32_e32 v186, v184, v186
	v_lshlrev_b32_e32 v182, 16, v107
	v_and_b32_e32 v183, 0xffff0000, v107
	v_mul_f32_e32 v184, v183, v183
	v_fmac_f32_e32 v184, v182, v182
	v_add_f32_e32 v186, v184, v186
	v_add_f32_e32 v28, v28, v186
	v_lshlrev_b32_e32 v182, 16, v108
	v_and_b32_e32 v183, 0xffff0000, v108
	v_mul_f32_e32 v184, v183, v183
	v_fmac_f32_e32 v184, v182, v182
	v_lshlrev_b32_e32 v182, 16, v109
	v_and_b32_e32 v183, 0xffff0000, v109
	v_mul_f32_e32 v185, v183, v183
	v_fmac_f32_e32 v185, v182, v182
	v_add_f32_e32 v186, v184, v185
	v_lshlrev_b32_e32 v182, 16, v110
	v_and_b32_e32 v183, 0xffff0000, v110
	v_mul_f32_e32 v184, v183, v183
	v_fmac_f32_e32 v184, v182, v182
	v_add_f32_e32 v186, v184, v186
	v_lshlrev_b32_e32 v182, 16, v111
	v_and_b32_e32 v183, 0xffff0000, v111
	v_mul_f32_e32 v184, v183, v183
	v_fmac_f32_e32 v184, v182, v182
	v_add_f32_e32 v186, v184, v186
	v_add_f32_e32 v28, v28, v186
	s_waitcnt vmcnt(8)
; __device__ __forceinline__ float bflo(unsigned w) { return __uint_as_float(w << 16); }
; __device__ __forceinline__ float bfhi(unsigned w) { return __uint_as_float(w & 0xffff0000u); }
; __device__ __forceinline__ void rstd_rows_b(const bf16* __restrict__ X, float* __restrict__ R, int gw, int NGW, int lane) {
;     for (int m = gw; m < S_; m += NGW) {
;         const v4u* xr = (const v4u*)(X + (size_t)m * DM) + lane; float s = 0.f;
; #pragma unroll
;         for (int j = 0; j < 4; ++j) { const v4u w = xr[64 * j];
;             const float a0 = bflo(w.x), a1 = bfhi(w.x), a2 = bflo(w.y), a3 = bfhi(w.y), a4 = bflo(w.z), a5 = bfhi(w.z), a6 = bflo(w.w), a7 = bfhi(w.w);
;             s += (a0 * a0 + a1 * a1) + (a2 * a2 + a3 * a3) + (a4 * a4 + a5 * a5) + (a6 * a6 + a7 * a7); }
;         const float rstd = 1.f / sqrtf(wave_sum(s) * (1.f / DM) + EPS_);
;         if (lane == 0) R[m] = rstd;
;     }
; }
	v_lshlrev_b32_e32 v182, 16, v112
	v_and_b32_e32 v183, 0xffff0000, v112
	v_mul_f32_e32 v184, v183, v183
	v_fmac_f32_e32 v184, v182, v182
	v_lshlrev_b32_e32 v182, 16, v113
	v_and_b32_e32 v183, 0xffff0000, v113
	v_mul_f32_e32 v185, v183, v183
	v_fmac_f32_e32 v185, v182, v182
	v_add_f32_e32 v29, v184, v185
	v_lshlrev_b32_e32 v182, 16, v114
	v_and_b32_e32 v183, 0xffff0000, v114
	v_mul_f32_e32 v184, v183, v183
	v_fmac_f32_e32 v184, v182, v182
	v_add_f32_e32 v29, v184, v29
	v_lshlrev_b32_e32 v182, 16, v115
	v_and_b32_e32 v183, 0xffff0000, v115
	v_mul_f32_e32 v184, v183, v183
	v_fmac_f32_e32 v184, v182, v182
	v_add_f32_e32 v29, v184, v29
	v_lshlrev_b32_e32 v182, 16, v116
	v_and_b32_e32 v183, 0xffff0000, v116
	v_mul_f32_e32 v184, v183, v183
	v_fmac_f32_e32 v184, v182, v182
	v_lshlrev_b32_e32 v182, 16, v117
	v_and_b32_e32 v183, 0xffff0000, v117
	v_mul_f32_e32 v185, v183, v183
	v_fmac_f32_e32 v185, v182, v182
	v_add_f32_e32 v186, v184, v185
	v_lshlrev_b32_e32 v182, 16, v118
	v_and_b32_e32 v183, 0xffff0000, v118
	v_mul_f32_e32 v184, v183, v183
	v_fmac_f32_e32 v184, v182, v182
	v_add_f32_e32 v186, v184, v186
	v_lshlrev_b32_e32 v182, 16, v119
	v_and_b32_e32 v183, 0xffff0000, v119
	v_mul_f32_e32 v184, v183, v183
	v_fmac_f32_e32 v184, v182, v182
	v_add_f32_e32 v186, v184, v186
	v_add_f32_e32 v29, v29, v186
	v_lshlrev_b32_e32 v182, 16, v120
	v_and_b32_e32 v183, 0xffff0000, v120
	v_mul_f32_e32 v184, v183, v183
	v_fmac_f32_e32 v184, v182, v182
	v_lshlrev_b32_e32 v182, 16, v121
	v_and_b32_e32 v183, 0xffff0000, v121
	v_mul_f32_e32 v185, v183, v183
	v_fmac_f32_e32 v185, v182, v182
	v_add_f32_e32 v186, v184, v185
	v_lshlrev_b32_e32 v182, 16, v122
	v_and_b32_e32 v183, 0xffff0000, v122
	v_mul_f32_e32 v184, v183, v183
	v_fmac_f32_e32 v184, v182, v182
	v_add_f32_e32 v186, v184, v186
	v_lshlrev_b32_e32 v182, 16, v123
	v_and_b32_e32 v183, 0xffff0000, v123
	v_mul_f32_e32 v184, v183, v183
	v_fmac_f32_e32 v184, v182, v182
	v_add_f32_e32 v186, v184, v186
	v_add_f32_e32 v29, v29, v186
	v_lshlrev_b32_e32 v182, 16, v124
	v_and_b32_e32 v183, 0xffff0000, v124
	v_mul_f32_e32 v184, v183, v183
	v_fmac_f32_e32 v184, v182, v182
	v_lshlrev_b32_e32 v182, 16, v125
	v_and_b32_e32 v183, 0xffff0000, v125
	v_mul_f32_e32 v185, v183, v183
	v_fmac_f32_e32 v185, v182, v182
	v_add_f32_e32 v186, v184, v185
	v_lshlrev_b32_e32 v182, 16, v126
	v_and_b32_e32 v183, 0xffff0000, v126
	v_mul_f32_e32 v184, v183, v183
	v_fmac_f32_e32 v184, v182, v182
	v_add_f32_e32 v186, v184, v186
	v_lshlrev_b32_e32 v182, 16, v127
	v_and_b32_e32 v183, 0xffff0000, v127
	v_mul_f32_e32 v184, v183, v183
	v_fmac_f32_e32 v184, v182, v182
	v_add_f32_e32 v186, v184, v186
	v_add_f32_e32 v29, v29, v186
	s_waitcnt vmcnt(4)
	v_lshlrev_b32_e32 v182, 16, v128
	v_and_b32_e32 v183, 0xffff0000, v128
	v_mul_f32_e32 v184, v183, v183
	v_fmac_f32_e32 v184, v182, v182
	v_lshlrev_b32_e32 v182, 16, v129
	v_and_b32_e32 v183, 0xffff0000, v129
	v_mul_f32_e32 v185, v183, v183
	v_fmac_f32_e32 v185, v182, v182
	v_add_f32_e32 v30, v184, v185
	v_lshlrev_b32_e32 v182, 16, v130
	v_and_b32_e32 v183, 0xffff0000, v130
	v_mul_f32_e32 v184, v183, v183
	v_fmac_f32_e32 v184, v182, v182
	v_add_f32_e32 v30, v184, v30
	v_lshlrev_b32_e32 v182, 16, v131
	v_and_b32_e32 v183, 0xffff0000, v131
	v_mul_f32_e32 v184, v183, v183
	v_fmac_f32_e32 v184, v182, v182
	v_add_f32_e32 v30, v184, v30
	v_lshlrev_b32_e32 v182, 16, v132
	v_and_b32_e32 v183, 0xffff0000, v132
	v_mul_f32_e32 v184, v183, v183
	v_fmac_f32_e32 v184, v182, v182
	v_lshlrev_b32_e32 v182, 16, v133
	v_and_b32_e32 v183, 0xffff0000, v133
	v_mul_f32_e32 v185, v183, v183
	v_fmac_f32_e32 v185, v182, v182
	v_add_f32_e32 v186, v184, v185
	v_lshlrev_b32_e32 v182, 16, v134
	v_and_b32_e32 v183, 0xffff0000, v134
	v_mul_f32_e32 v184, v183, v183
	v_fmac_f32_e32 v184, v182, v182
	v_add_f32_e32 v186, v184, v186
	v_lshlrev_b32_e32 v182, 16, v135
	v_and_b32_e32 v183, 0xffff0000, v135
	v_mul_f32_e32 v184, v183, v183
	v_fmac_f32_e32 v184, v182, v182
	v_add_f32_e32 v186, v184, v186
	v_add_f32_e32 v30, v30, v186
	v_lshlrev_b32_e32 v182, 16, v136
	v_and_b32_e32 v183, 0xffff0000, v136
	v_mul_f32_e32 v184, v183, v183
	v_fmac_f32_e32 v184, v182, v182
	v_lshlrev_b32_e32 v182, 16, v137
	v_and_b32_e32 v183, 0xffff0000, v137
	v_mul_f32_e32 v185, v183, v183
	v_fmac_f32_e32 v185, v182, v182
	v_add_f32_e32 v186, v184, v185
	v_lshlrev_b32_e32 v182, 16, v138
	v_and_b32_e32 v183, 0xffff0000, v138
	v_mul_f32_e32 v184, v183, v183
	v_fmac_f32_e32 v184, v182, v182
	v_add_f32_e32 v186, v184, v186
	v_lshlrev_b32_e32 v182, 16, v139
	v_and_b32_e32 v183, 0xffff0000, v139
	v_mul_f32_e32 v184, v183, v183
	v_fmac_f32_e32 v184, v182, v182
	v_add_f32_e32 v186, v184, v186
	v_add_f32_e32 v30, v30, v186
	v_lshlrev_b32_e32 v182, 16, v140
	v_and_b32_e32 v183, 0xffff0000, v140
	v_mul_f32_e32 v184, v183, v183
	v_fmac_f32_e32 v184, v182, v182
	v_lshlrev_b32_e32 v182, 16, v141
	v_and_b32_e32 v183, 0xffff0000, v141
	v_mul_f32_e32 v185, v183, v183
	v_fmac_f32_e32 v185, v182, v182
	v_add_f32_e32 v186, v184, v185
	v_lshlrev_b32_e32 v182, 16, v142
	v_and_b32_e32 v183, 0xffff0000, v142
	v_mul_f32_e32 v184, v183, v183
	v_fmac_f32_e32 v184, v182, v182
	v_add_f32_e32 v186, v184, v186
	v_lshlrev_b32_e32 v182, 16, v143
	v_and_b32_e32 v183, 0xffff0000, v143
	v_mul_f32_e32 v184, v183, v183
	v_fmac_f32_e32 v184, v182, v182
	v_add_f32_e32 v186, v184, v186
	v_add_f32_e32 v30, v30, v186
	s_waitcnt vmcnt(0)
; __device__ __forceinline__ float bflo(unsigned w) { return __uint_as_float(w << 16); }
; __device__ __forceinline__ float bfhi(unsigned w) { return __uint_as_float(w & 0xffff0000u); }
; __device__ __forceinline__ float wave_sum(float v) {
; #pragma unroll
;     for (int o = 1; o < 64; o <<= 1) v += __shfl_xor(v, o);
;     return v;
; }
; __device__ __forceinline__ void rstd_rows_b(const bf16* __restrict__ X, float* __restrict__ R, int gw, int NGW, int lane) {
;     for (int m = gw; m < S_; m += NGW) {
;         const v4u* xr = (const v4u*)(X + (size_t)m * DM) + lane; float s = 0.f;
; #pragma unroll
;         for (int j = 0; j < 4; ++j) { const v4u w = xr[64 * j];
;             const float a0 = bflo(w.x), a1 = bfhi(w.x), a2 = bflo(w.y), a3 = bfhi(w.y), a4 = bflo(w.z), a5 = bfhi(w.z), a6 = bflo(w.w), a7 = bfhi(w.w);
;             s += (a0 * a0 + a1 * a1) + (a2 * a2 + a3 * a3) + (a4 * a4 + a5 * a5) + (a6 * a6 + a7 * a7); }
;         const float rstd = 1.f / sqrtf(wave_sum(s) * (1.f / DM) + EPS_);
;         if (lane == 0) R[m] = rstd;
;     }
; }
	v_lshlrev_b32_e32 v182, 16, v144
	v_and_b32_e32 v183, 0xffff0000, v144
	v_mul_f32_e32 v184, v183, v183
	v_fmac_f32_e32 v184, v182, v182
	v_lshlrev_b32_e32 v182, 16, v145
	v_and_b32_e32 v183, 0xffff0000, v145
	v_mul_f32_e32 v185, v183, v183
	v_fmac_f32_e32 v185, v182, v182
	v_add_f32_e32 v31, v184, v185
	v_lshlrev_b32_e32 v182, 16, v146
	v_and_b32_e32 v183, 0xffff0000, v146
	v_mul_f32_e32 v184, v183, v183
	v_fmac_f32_e32 v184, v182, v182
	v_add_f32_e32 v31, v184, v31
	v_lshlrev_b32_e32 v182, 16, v147
	v_and_b32_e32 v183, 0xffff0000, v147
	v_mul_f32_e32 v184, v183, v183
	v_fmac_f32_e32 v184, v182, v182
	v_add_f32_e32 v31, v184, v31
	v_lshlrev_b32_e32 v182, 16, v148
	v_and_b32_e32 v183, 0xffff0000, v148
	v_mul_f32_e32 v184, v183, v183
	v_fmac_f32_e32 v184, v182, v182
	v_lshlrev_b32_e32 v182, 16, v149
	v_and_b32_e32 v183, 0xffff0000, v149
	v_mul_f32_e32 v185, v183, v183
	v_fmac_f32_e32 v185, v182, v182
	v_add_f32_e32 v186, v184, v185
	v_lshlrev_b32_e32 v182, 16, v150
	v_and_b32_e32 v183, 0xffff0000, v150
	v_mul_f32_e32 v184, v183, v183
	v_fmac_f32_e32 v184, v182, v182
	v_add_f32_e32 v186, v184, v186
	v_lshlrev_b32_e32 v182, 16, v151
	v_and_b32_e32 v183, 0xffff0000, v151
	v_mul_f32_e32 v184, v183, v183
	v_fmac_f32_e32 v184, v182, v182
	v_add_f32_e32 v186, v184, v186
	v_add_f32_e32 v31, v31, v186
	v_lshlrev_b32_e32 v182, 16, v152
	v_and_b32_e32 v183, 0xffff0000, v152
	v_mul_f32_e32 v184, v183, v183
	v_fmac_f32_e32 v184, v182, v182
	v_lshlrev_b32_e32 v182, 16, v153
	v_and_b32_e32 v183, 0xffff0000, v153
	v_mul_f32_e32 v185, v183, v183
	v_fmac_f32_e32 v185, v182, v182
	v_add_f32_e32 v186, v184, v185
	v_lshlrev_b32_e32 v182, 16, v154
	v_and_b32_e32 v183, 0xffff0000, v154
	v_mul_f32_e32 v184, v183, v183
	v_fmac_f32_e32 v184, v182, v182
	v_add_f32_e32 v186, v184, v186
	v_lshlrev_b32_e32 v182, 16, v155
	v_and_b32_e32 v183, 0xffff0000, v155
	v_mul_f32_e32 v184, v183, v183
	v_fmac_f32_e32 v184, v182, v182
	v_add_f32_e32 v186, v184, v186
	v_add_f32_e32 v31, v31, v186
	v_lshlrev_b32_e32 v182, 16, v156
	v_and_b32_e32 v183, 0xffff0000, v156
	v_mul_f32_e32 v184, v183, v183
	v_fmac_f32_e32 v184, v182, v182
	v_lshlrev_b32_e32 v182, 16, v157
	v_and_b32_e32 v183, 0xffff0000, v157
	v_mul_f32_e32 v185, v183, v183
	v_fmac_f32_e32 v185, v182, v182
	v_add_f32_e32 v186, v184, v185
	v_lshlrev_b32_e32 v182, 16, v158
	v_and_b32_e32 v183, 0xffff0000, v158
	v_mul_f32_e32 v184, v183, v183
	v_fmac_f32_e32 v184, v182, v182
	v_add_f32_e32 v186, v184, v186
	v_lshlrev_b32_e32 v182, 16, v159
	v_and_b32_e32 v183, 0xffff0000, v159
	v_mul_f32_e32 v184, v183, v183
	v_fmac_f32_e32 v184, v182, v182
	v_add_f32_e32 v186, v184, v186
	v_add_f32_e32 v31, v31, v186
	ds_bpermute_b32 v174, v0, v24
	ds_bpermute_b32 v175, v0, v25
	ds_bpermute_b32 v176, v0, v26
	ds_bpermute_b32 v177, v0, v27
	ds_bpermute_b32 v178, v0, v28
	ds_bpermute_b32 v179, v0, v29
	ds_bpermute_b32 v180, v0, v30
	ds_bpermute_b32 v181, v0, v31
	s_waitcnt lgkmcnt(0)
	v_add_f32_e32 v24, v24, v174
	v_add_f32_e32 v25, v25, v175
	v_add_f32_e32 v26, v26, v176
	v_add_f32_e32 v27, v27, v177
	v_add_f32_e32 v28, v28, v178
	v_add_f32_e32 v29, v29, v179
	v_add_f32_e32 v30, v30, v180
	v_add_f32_e32 v31, v31, v181
	ds_bpermute_b32 v174, v12, v24
	ds_bpermute_b32 v175, v12, v25
	ds_bpermute_b32 v176, v12, v26
	ds_bpermute_b32 v177, v12, v27
	ds_bpermute_b32 v178, v12, v28
	ds_bpermute_b32 v179, v12, v29
	ds_bpermute_b32 v180, v12, v30
	ds_bpermute_b32 v181, v12, v31
	s_waitcnt lgkmcnt(0)
	v_add_f32_e32 v24, v24, v174
	v_add_f32_e32 v25, v25, v175
	v_add_f32_e32 v26, v26, v176
	v_add_f32_e32 v27, v27, v177
	v_add_f32_e32 v28, v28, v178
	v_add_f32_e32 v29, v29, v179
	v_add_f32_e32 v30, v30, v180
	v_add_f32_e32 v31, v31, v181
	ds_bpermute_b32 v174, v13, v24
	ds_bpermute_b32 v175, v13, v25
	ds_bpermute_b32 v176, v13, v26
	ds_bpermute_b32 v177, v13, v27
	ds_bpermute_b32 v178, v13, v28
	ds_bpermute_b32 v179, v13, v29
	ds_bpermute_b32 v180, v13, v30
	ds_bpermute_b32 v181, v13, v31
	s_waitcnt lgkmcnt(0)
	v_add_f32_e32 v24, v24, v174
	v_add_f32_e32 v25, v25, v175
	v_add_f32_e32 v26, v26, v176
	v_add_f32_e32 v27, v27, v177
	v_add_f32_e32 v28, v28, v178
	v_add_f32_e32 v29, v29, v179
	v_add_f32_e32 v30, v30, v180
	v_add_f32_e32 v31, v31, v181
	ds_bpermute_b32 v174, v14, v24
	ds_bpermute_b32 v175, v14, v25
	ds_bpermute_b32 v176, v14, v26
	ds_bpermute_b32 v177, v14, v27
	ds_bpermute_b32 v178, v14, v28
	ds_bpermute_b32 v179, v14, v29
	ds_bpermute_b32 v180, v14, v30
	ds_bpermute_b32 v181, v14, v31
	s_waitcnt lgkmcnt(0)
	v_add_f32_e32 v24, v24, v174
	v_add_f32_e32 v25, v25, v175
	v_add_f32_e32 v26, v26, v176
	v_add_f32_e32 v27, v27, v177
	v_add_f32_e32 v28, v28, v178
	v_add_f32_e32 v29, v29, v179
	v_add_f32_e32 v30, v30, v180
	v_add_f32_e32 v31, v31, v181
	ds_bpermute_b32 v174, v15, v24
	ds_bpermute_b32 v175, v15, v25
	ds_bpermute_b32 v176, v15, v26
	ds_bpermute_b32 v177, v15, v27
	ds_bpermute_b32 v178, v15, v28
	ds_bpermute_b32 v179, v15, v29
	ds_bpermute_b32 v180, v15, v30
	ds_bpermute_b32 v181, v15, v31
	s_waitcnt lgkmcnt(0)
	v_add_f32_e32 v24, v24, v174
	v_add_f32_e32 v25, v25, v175
	v_add_f32_e32 v26, v26, v176
	v_add_f32_e32 v27, v27, v177
	v_add_f32_e32 v28, v28, v178
	v_add_f32_e32 v29, v29, v179
	v_add_f32_e32 v30, v30, v180
	v_add_f32_e32 v31, v31, v181
	ds_bpermute_b32 v174, v16, v24
	ds_bpermute_b32 v175, v16, v25
	ds_bpermute_b32 v176, v16, v26
	ds_bpermute_b32 v177, v16, v27
	ds_bpermute_b32 v178, v16, v28
	ds_bpermute_b32 v179, v16, v29
	ds_bpermute_b32 v180, v16, v30
	ds_bpermute_b32 v181, v16, v31
	s_waitcnt lgkmcnt(0)
	v_add_f32_e32 v24, v24, v174
	v_add_f32_e32 v25, v25, v175
	v_add_f32_e32 v26, v26, v176
	v_add_f32_e32 v27, v27, v177
	v_add_f32_e32 v28, v28, v178
	v_add_f32_e32 v29, v29, v179
	v_add_f32_e32 v30, v30, v180
	v_add_f32_e32 v31, v31, v181
	s_and_saveexec_b64 s[6:7], s[40:41]
	s_cbranch_execz .Lrstd7_skip
; __device__ __forceinline__ void rstd_rows_b(const bf16* __restrict__ X, float* __restrict__ R, int gw, int NGW, int lane) {
;     ...
;         const float rstd = 1.f / sqrtf(wave_sum(s) * (1.f / DM) + EPS_);
;         if (lane == 0) R[m] = rstd;
	v_mov_b32_e32 v20, v10
	v_mov_b32_e32 v21, v11
	v_fmamk_f32 v24, v24, 0x3a000000, v190
	v_mul_f32_e32 v182, 0x4f800000, v24
	v_cmp_gt_f32_e32 vcc, s73, v24
	s_nop 1
	v_cndmask_b32_e32 v24, v24, v182, vcc
	v_sqrt_f32_e32 v182, v24
	s_nop 0
	v_add_u32_e32 v183, -1, v182
	v_fma_f32 v185, -v183, v182, v24
	v_add_u32_e32 v184, 1, v182
	v_cmp_ge_f32_e64 s[42:43], 0, v185
	s_nop 1
	v_cndmask_b32_e64 v183, v182, v183, s[42:43]
	v_fma_f32 v182, -v184, v182, v24
	v_cmp_lt_f32_e64 s[42:43], 0, v182
	s_nop 1
	v_cndmask_b32_e64 v182, v183, v184, s[42:43]
	v_mul_f32_e32 v183, 0x37800000, v182
	v_cndmask_b32_e32 v182, v182, v183, vcc
	v_cmp_class_f32_e32 vcc, v24, v191
	s_nop 1
	v_cndmask_b32_e32 v24, v182, v24, vcc
	v_div_scale_f32 v182, s[2:3], v24, v24, 1.0
	v_rcp_f32_e32 v183, v182
	s_nop 0
	v_fma_f32 v184, -v182, v183, 1.0
	v_fmac_f32_e32 v183, v184, v183
	v_div_scale_f32 v184, vcc, 1.0, v24, 1.0
	v_mul_f32_e32 v185, v184, v183
	v_fma_f32 v186, -v182, v185, v184
	v_fmac_f32_e32 v185, v186, v183
	v_fma_f32 v182, -v182, v185, v184
	v_div_fmas_f32 v182, v182, v183, v185
	v_div_fixup_f32 v24, v182, v24, 1.0
	global_store_dword v[20:21], v24, off
	v_lshl_add_u64 v[20:21], v[20:21], 0, v[4:5]
	v_fmamk_f32 v25, v25, 0x3a000000, v190
	v_mul_f32_e32 v182, 0x4f800000, v25
	v_cmp_gt_f32_e32 vcc, s73, v25
	s_nop 1
	v_cndmask_b32_e32 v25, v25, v182, vcc
	v_sqrt_f32_e32 v182, v25
	s_nop 0
	v_add_u32_e32 v183, -1, v182
	v_fma_f32 v185, -v183, v182, v25
	v_add_u32_e32 v184, 1, v182
	v_cmp_ge_f32_e64 s[42:43], 0, v185
	s_nop 1
	v_cndmask_b32_e64 v183, v182, v183, s[42:43]
	v_fma_f32 v182, -v184, v182, v25
	v_cmp_lt_f32_e64 s[42:43], 0, v182
	s_nop 1
	v_cndmask_b32_e64 v182, v183, v184, s[42:43]
	v_mul_f32_e32 v183, 0x37800000, v182
	v_cndmask_b32_e32 v182, v182, v183, vcc
	v_cmp_class_f32_e32 vcc, v25, v191
	s_nop 1
	v_cndmask_b32_e32 v25, v182, v25, vcc
	v_div_scale_f32 v182, s[2:3], v25, v25, 1.0
	v_rcp_f32_e32 v183, v182
	s_nop 0
	v_fma_f32 v184, -v182, v183, 1.0
	v_fmac_f32_e32 v183, v184, v183
	v_div_scale_f32 v184, vcc, 1.0, v25, 1.0
	v_mul_f32_e32 v185, v184, v183
	v_fma_f32 v186, -v182, v185, v184
	v_fmac_f32_e32 v185, v186, v183
	v_fma_f32 v182, -v182, v185, v184
	v_div_fmas_f32 v182, v182, v183, v185
	v_div_fixup_f32 v25, v182, v25, 1.0
	global_store_dword v[20:21], v25, off
	v_lshl_add_u64 v[20:21], v[20:21], 0, v[4:5]
	v_fmamk_f32 v26, v26, 0x3a000000, v190
	v_mul_f32_e32 v182, 0x4f800000, v26
	v_cmp_gt_f32_e32 vcc, s73, v26
	s_nop 1
	v_cndmask_b32_e32 v26, v26, v182, vcc
	v_sqrt_f32_e32 v182, v26
	s_nop 0
	v_add_u32_e32 v183, -1, v182
	v_fma_f32 v185, -v183, v182, v26
	v_add_u32_e32 v184, 1, v182
	v_cmp_ge_f32_e64 s[42:43], 0, v185
	s_nop 1
	v_cndmask_b32_e64 v183, v182, v183, s[42:43]
	v_fma_f32 v182, -v184, v182, v26
	v_cmp_lt_f32_e64 s[42:43], 0, v182
	s_nop 1
	v_cndmask_b32_e64 v182, v183, v184, s[42:43]
	v_mul_f32_e32 v183, 0x37800000, v182
	v_cndmask_b32_e32 v182, v182, v183, vcc
	v_cmp_class_f32_e32 vcc, v26, v191
	s_nop 1
	v_cndmask_b32_e32 v26, v182, v26, vcc
	v_div_scale_f32 v182, s[2:3], v26, v26, 1.0
	v_rcp_f32_e32 v183, v182
	s_nop 0
	v_fma_f32 v184, -v182, v183, 1.0
	v_fmac_f32_e32 v183, v184, v183
	v_div_scale_f32 v184, vcc, 1.0, v26, 1.0
	v_mul_f32_e32 v185, v184, v183
	v_fma_f32 v186, -v182, v185, v184
	v_fmac_f32_e32 v185, v186, v183
	v_fma_f32 v182, -v182, v185, v184
	v_div_fmas_f32 v182, v182, v183, v185
	v_div_fixup_f32 v26, v182, v26, 1.0
	global_store_dword v[20:21], v26, off
	v_lshl_add_u64 v[20:21], v[20:21], 0, v[4:5]
	v_fmamk_f32 v27, v27, 0x3a000000, v190
	v_mul_f32_e32 v182, 0x4f800000, v27
	v_cmp_gt_f32_e32 vcc, s73, v27
	s_nop 1
	v_cndmask_b32_e32 v27, v27, v182, vcc
	v_sqrt_f32_e32 v182, v27
	s_nop 0
	v_add_u32_e32 v183, -1, v182
	v_fma_f32 v185, -v183, v182, v27
	v_add_u32_e32 v184, 1, v182
	v_cmp_ge_f32_e64 s[42:43], 0, v185
	s_nop 1
	v_cndmask_b32_e64 v183, v182, v183, s[42:43]
	v_fma_f32 v182, -v184, v182, v27
	v_cmp_lt_f32_e64 s[42:43], 0, v182
	s_nop 1
	v_cndmask_b32_e64 v182, v183, v184, s[42:43]
	v_mul_f32_e32 v183, 0x37800000, v182
	v_cndmask_b32_e32 v182, v182, v183, vcc
	v_cmp_class_f32_e32 vcc, v27, v191
	s_nop 1
	v_cndmask_b32_e32 v27, v182, v27, vcc
	v_div_scale_f32 v182, s[2:3], v27, v27, 1.0
	v_rcp_f32_e32 v183, v182
	s_nop 0
	v_fma_f32 v184, -v182, v183, 1.0
	v_fmac_f32_e32 v183, v184, v183
	v_div_scale_f32 v184, vcc, 1.0, v27, 1.0
	v_mul_f32_e32 v185, v184, v183
	v_fma_f32 v186, -v182, v185, v184
	v_fmac_f32_e32 v185, v186, v183
	v_fma_f32 v182, -v182, v185, v184
	v_div_fmas_f32 v182, v182, v183, v185
	v_div_fixup_f32 v27, v182, v27, 1.0
	global_store_dword v[20:21], v27, off
	v_lshl_add_u64 v[20:21], v[20:21], 0, v[4:5]
	v_fmamk_f32 v28, v28, 0x3a000000, v190
	v_mul_f32_e32 v182, 0x4f800000, v28
	v_cmp_gt_f32_e32 vcc, s73, v28
; __device__ __forceinline__ void rstd_rows_b(const bf16* __restrict__ X, float* __restrict__ R, int gw, int NGW, int lane) {
;     ...
;         const float rstd = 1.f / sqrtf(wave_sum(s) * (1.f / DM) + EPS_);
;         if (lane == 0) R[m] = rstd;
	s_nop 1
	v_cndmask_b32_e32 v28, v28, v182, vcc
	v_sqrt_f32_e32 v182, v28
	s_nop 0
	v_add_u32_e32 v183, -1, v182
	v_fma_f32 v185, -v183, v182, v28
	v_add_u32_e32 v184, 1, v182
	v_cmp_ge_f32_e64 s[42:43], 0, v185
	s_nop 1
	v_cndmask_b32_e64 v183, v182, v183, s[42:43]
	v_fma_f32 v182, -v184, v182, v28
	v_cmp_lt_f32_e64 s[42:43], 0, v182
	s_nop 1
	v_cndmask_b32_e64 v182, v183, v184, s[42:43]
	v_mul_f32_e32 v183, 0x37800000, v182
	v_cndmask_b32_e32 v182, v182, v183, vcc
	v_cmp_class_f32_e32 vcc, v28, v191
	s_nop 1
	v_cndmask_b32_e32 v28, v182, v28, vcc
	v_div_scale_f32 v182, s[2:3], v28, v28, 1.0
	v_rcp_f32_e32 v183, v182
	s_nop 0
	v_fma_f32 v184, -v182, v183, 1.0
	v_fmac_f32_e32 v183, v184, v183
	v_div_scale_f32 v184, vcc, 1.0, v28, 1.0
	v_mul_f32_e32 v185, v184, v183
	v_fma_f32 v186, -v182, v185, v184
	v_fmac_f32_e32 v185, v186, v183
	v_fma_f32 v182, -v182, v185, v184
	v_div_fmas_f32 v182, v182, v183, v185
	v_div_fixup_f32 v28, v182, v28, 1.0
	global_store_dword v[20:21], v28, off
	v_lshl_add_u64 v[20:21], v[20:21], 0, v[4:5]
	v_fmamk_f32 v29, v29, 0x3a000000, v190
	v_mul_f32_e32 v182, 0x4f800000, v29
	v_cmp_gt_f32_e32 vcc, s73, v29
	s_nop 1
	v_cndmask_b32_e32 v29, v29, v182, vcc
	v_sqrt_f32_e32 v182, v29
	s_nop 0
	v_add_u32_e32 v183, -1, v182
	v_fma_f32 v185, -v183, v182, v29
	v_add_u32_e32 v184, 1, v182
	v_cmp_ge_f32_e64 s[42:43], 0, v185
	s_nop 1
	v_cndmask_b32_e64 v183, v182, v183, s[42:43]
	v_fma_f32 v182, -v184, v182, v29
	v_cmp_lt_f32_e64 s[42:43], 0, v182
	s_nop 1
	v_cndmask_b32_e64 v182, v183, v184, s[42:43]
	v_mul_f32_e32 v183, 0x37800000, v182
	v_cndmask_b32_e32 v182, v182, v183, vcc
	v_cmp_class_f32_e32 vcc, v29, v191
	s_nop 1
	v_cndmask_b32_e32 v29, v182, v29, vcc
	v_div_scale_f32 v182, s[2:3], v29, v29, 1.0
	v_rcp_f32_e32 v183, v182
	s_nop 0
	v_fma_f32 v184, -v182, v183, 1.0
	v_fmac_f32_e32 v183, v184, v183
	v_div_scale_f32 v184, vcc, 1.0, v29, 1.0
	v_mul_f32_e32 v185, v184, v183
	v_fma_f32 v186, -v182, v185, v184
	v_fmac_f32_e32 v185, v186, v183
	v_fma_f32 v182, -v182, v185, v184
	v_div_fmas_f32 v182, v182, v183, v185
	v_div_fixup_f32 v29, v182, v29, 1.0
	global_store_dword v[20:21], v29, off
	v_lshl_add_u64 v[20:21], v[20:21], 0, v[4:5]
	v_fmamk_f32 v30, v30, 0x3a000000, v190
	v_mul_f32_e32 v182, 0x4f800000, v30
	v_cmp_gt_f32_e32 vcc, s73, v30
	s_nop 1
	v_cndmask_b32_e32 v30, v30, v182, vcc
	v_sqrt_f32_e32 v182, v30
	s_nop 0
	v_add_u32_e32 v183, -1, v182
	v_fma_f32 v185, -v183, v182, v30
	v_add_u32_e32 v184, 1, v182
	v_cmp_ge_f32_e64 s[42:43], 0, v185
	s_nop 1
	v_cndmask_b32_e64 v183, v182, v183, s[42:43]
	v_fma_f32 v182, -v184, v182, v30
	v_cmp_lt_f32_e64 s[42:43], 0, v182
	s_nop 1
	v_cndmask_b32_e64 v182, v183, v184, s[42:43]
	v_mul_f32_e32 v183, 0x37800000, v182
	v_cndmask_b32_e32 v182, v182, v183, vcc
	v_cmp_class_f32_e32 vcc, v30, v191
	s_nop 1
	v_cndmask_b32_e32 v30, v182, v30, vcc
	v_div_scale_f32 v182, s[2:3], v30, v30, 1.0
	v_rcp_f32_e32 v183, v182
	s_nop 0
	v_fma_f32 v184, -v182, v183, 1.0
	v_fmac_f32_e32 v183, v184, v183
	v_div_scale_f32 v184, vcc, 1.0, v30, 1.0
	v_mul_f32_e32 v185, v184, v183
	v_fma_f32 v186, -v182, v185, v184
	v_fmac_f32_e32 v185, v186, v183
	v_fma_f32 v182, -v182, v185, v184
	v_div_fmas_f32 v182, v182, v183, v185
	v_div_fixup_f32 v30, v182, v30, 1.0
	global_store_dword v[20:21], v30, off
	v_lshl_add_u64 v[20:21], v[20:21], 0, v[4:5]
	v_fmamk_f32 v31, v31, 0x3a000000, v190
	v_mul_f32_e32 v182, 0x4f800000, v31
	v_cmp_gt_f32_e32 vcc, s73, v31
	s_nop 1
	v_cndmask_b32_e32 v31, v31, v182, vcc
	v_sqrt_f32_e32 v182, v31
	s_nop 0
	v_add_u32_e32 v183, -1, v182
	v_fma_f32 v185, -v183, v182, v31
	v_add_u32_e32 v184, 1, v182
	v_cmp_ge_f32_e64 s[42:43], 0, v185
	s_nop 1
	v_cndmask_b32_e64 v183, v182, v183, s[42:43]
	v_fma_f32 v182, -v184, v182, v31
	v_cmp_lt_f32_e64 s[42:43], 0, v182
	s_nop 1
	v_cndmask_b32_e64 v182, v183, v184, s[42:43]
	v_mul_f32_e32 v183, 0x37800000, v182
	v_cndmask_b32_e32 v182, v182, v183, vcc
	v_cmp_class_f32_e32 vcc, v31, v191
	s_nop 1
	v_cndmask_b32_e32 v31, v182, v31, vcc
	v_div_scale_f32 v182, s[2:3], v31, v31, 1.0
	v_rcp_f32_e32 v183, v182
	s_nop 0
	v_fma_f32 v184, -v182, v183, 1.0
	v_fmac_f32_e32 v183, v184, v183
	v_div_scale_f32 v184, vcc, 1.0, v31, 1.0
	v_mul_f32_e32 v185, v184, v183
	v_fma_f32 v186, -v182, v185, v184
	v_fmac_f32_e32 v185, v186, v183
	v_fma_f32 v182, -v182, v185, v184
	v_div_fmas_f32 v182, v182, v183, v185
	v_div_fixup_f32 v31, v182, v31, 1.0
	global_store_dword v[20:21], v31, off
.Lrstd7_skip:
	s_or_b64 exec, exec, s[6:7]
	v_lshl_add_u32 v3, v2, 3, v3
	v_lshlrev_b64 v[20:21], 3, v[4:5]
	v_lshl_add_u64 v[10:11], v[10:11], 0, v[20:21]
	v_lshlrev_b64 v[20:21], 3, v[8:9]
	v_lshl_add_u64 v[6:7], v[6:7], 0, v[20:21]
	v_cmp_gt_i32_e32 vcc, s46, v3
	s_cbranch_vccnz .Lrstd7_batch
	s_branch .LBB0_1668
